# as previous, V^T tile LDS write issued before the row-sum adds so its latency is covered before the tile barrier
# baseline (speedup 1.0000x reference)
; #define AT_QK_LD0(kb_) do { if constexpr (NEGM) { const LAS unsigned char* kbp_ = Kl + (kb_) * KBUF + r32 * KROWB + hi * 16; AT_KLD2(0); __builtin_amdgcn_sched_barrier(0); } } while (0)
; template <int DQK, int DV, int RH, bool NEGM> ...
;     ...
;     const int NT = nkv / 64;
;     AT_GLOAD(0); AT_LSTORE(0, 0); __syncthreads();
;     int vs_prev = 2, vs_cur = 0, vs_next = 1;
;     if (!grpB) {
;         for (int t = 0; t < NT; ++t) {
;             const int kb = t & 1;
;             if (t + 1 < NT) AT_GLOAD(t + 1);
;             f32x16 p[RH][2];
;             AT_QK_LD0(kb); AT_QK(kb); AT_VLOAD(vs_cur); AT_SOFTMAX(); AT_PV(vs_cur);
;             if (t + 1 < NT) AT_LSTORE(kb ^ 1, vs_next);
;             __syncthreads();
;             vs_prev = vs_cur; vs_cur = vs_next; vs_next = (vs_next == 2) ? 0 : vs_next + 1;
.Lmla_norescale_o:
	v_exp_f32_e32 v160, v64
	v_exp_f32_e32 v161, v65
	v_exp_f32_e32 v64, v66
	v_exp_f32_e32 v65, v67
	v_exp_f32_e32 v68, v68
	v_exp_f32_e32 v69, v69
	v_exp_f32_e32 v66, v70
	v_exp_f32_e32 v67, v71
	v_cvt_pk_bf16_f32 v176, v160, v161
	v_cvt_pk_bf16_f32 v177, v64, v65
	v_cvt_pk_bf16_f32 v178, v68, v69
	v_cvt_pk_bf16_f32 v179, v66, v67
	v_exp_f32_e32 v70, v74
	v_exp_f32_e32 v71, v75
	s_waitcnt lgkmcnt(0)
	v_mfma_f32_32x32x16_bf16 v[16:31], v[136:139], v[176:179], v[16:31]
	v_exp_f32_e32 v136, v72
	v_exp_f32_e32 v137, v73
	v_exp_f32_e32 v74, v76
	v_exp_f32_e32 v75, v77
	v_exp_f32_e32 v72, v78
	v_exp_f32_e32 v73, v79
	v_exp_f32_e32 v76, v48
	v_mfma_f32_32x32x16_bf16 v[0:15], v[144:147], v[176:179], v[0:15]
	v_cvt_pk_bf16_f32 v144, v136, v137
	v_cvt_pk_bf16_f32 v145, v70, v71
	v_cvt_pk_bf16_f32 v146, v74, v75
	v_cvt_pk_bf16_f32 v147, v72, v73
	v_exp_f32_e32 v77, v49
	v_exp_f32_e32 v48, v50
	v_exp_f32_e32 v49, v51
	v_mfma_f32_32x32x16_bf16 v[16:31], v[124:127], v[144:147], v[16:31]
	v_exp_f32_e32 v52, v52
	v_exp_f32_e32 v53, v53
	v_exp_f32_e32 v50, v54
	v_exp_f32_e32 v51, v55
	v_cvt_pk_bf16_f32 v124, v76, v77
	v_cvt_pk_bf16_f32 v125, v48, v49
	v_cvt_pk_bf16_f32 v126, v52, v53
	v_mfma_f32_32x32x16_bf16 v[0:15], v[140:143], v[144:147], v[0:15]
	v_cvt_pk_bf16_f32 v127, v50, v51
	v_exp_f32_e32 v78, v56
	v_exp_f32_e32 v79, v57
	v_exp_f32_e32 v54, v58
	v_exp_f32_e32 v55, v59
	v_exp_f32_e32 v58, v60
	v_exp_f32_e32 v59, v61
	v_mfma_f32_32x32x16_bf16 v[16:31], v[132:135], v[124:127], v[16:31]
	v_exp_f32_e32 v56, v62
	v_exp_f32_e32 v57, v63
	v_cvt_pk_bf16_f32 v60, v78, v79
	v_cvt_pk_bf16_f32 v61, v54, v55
	v_cvt_pk_bf16_f32 v62, v58, v59
	v_cvt_pk_bf16_f32 v63, v56, v57
	v_mfma_f32_32x32x16_bf16 v[0:15], v[128:131], v[124:127], v[0:15]
	v_mfma_f32_32x32x16_bf16 v[16:31], v[120:123], v[60:63], v[16:31]
	v_mfma_f32_32x32x16_bf16 v[0:15], v[116:119], v[60:63], v[0:15]
	s_waitcnt vmcnt(1)
	ds_write_b128 v244, v[104:107]
	s_mov_b64 exec, s[8:9]
	ds_write_b128 v245, v[108:111]
	s_mov_b64 exec, -1
	s_mul_i32 s21, s42, 0x2400
	v_add_u32_e32 v242, s21, v243
	s_waitcnt vmcnt(0)
	ds_write2_b64 v242, v[112:113], v[114:115] offset1:2
	v_pk_add_f32 v[48:49], v[64:65], v[48:49]
	v_pk_add_f32 v[60:61], v[160:161], v[76:77]
	v_pk_add_f32 v[48:49], v[152:153], v[48:49]
	v_pk_add_f32 v[50:51], v[66:67], v[50:51]
	v_pk_add_f32 v[60:61], v[150:151], v[60:61]
	v_pk_add_f32 v[52:53], v[68:69], v[52:53]
	v_pk_add_f32 v[48:49], v[50:51], v[48:49]
	v_pk_add_f32 v[50:51], v[70:71], v[54:55]
	v_pk_add_f32 v[52:53], v[52:53], v[60:61]
	v_pk_add_f32 v[60:61], v[136:137], v[78:79]
	v_pk_add_f32 v[48:49], v[50:51], v[48:49]
	v_pk_add_f32 v[50:51], v[72:73], v[56:57]
	s_add_i32 s40, s42, 1
	v_pk_add_f32 v[52:53], v[60:61], v[52:53]
	v_pk_add_f32 v[58:59], v[74:75], v[58:59]
	v_pk_add_f32 v[152:153], v[50:51], v[48:49]
	s_cmp_lg_u32 s42, 2
	v_pk_add_f32 v[150:151], v[58:59], v[52:53]
	s_cselect_b32 s40, s40, 0
	s_cmp_lg_u32 s43, 63
	s_waitcnt lgkmcnt(0)
	s_barrier
	s_mov_b32 s21, s42
	s_mov_b32 s42, s40
	global_load_dwordx4 v[104:107], v154, s[98:99]
	s_mov_b64 exec, s[8:9]
	global_load_dwordx4 v[108:111], v156, s[98:99]
	s_mov_b64 exec, -1
	global_load_dwordx4 v[112:115], v158, s[100:101]
	s_add_u32 s98, s98, 0x18000
	s_addc_u32 s99, s99, 0
	s_add_u32 s100, s100, 0x80
	s_addc_u32 s101, s101, 0
	ds_read_b128 v[48:51], v169
	ds_read_b128 v[52:55], v169 offset:32
	ds_read_b128 v[116:119], v169 offset:6656
	ds_read_b128 v[120:123], v169 offset:6688
	s_waitcnt lgkmcnt(3)
	v_mfma_f32_32x32x16_bf16 v[64:79], v[48:51], v[100:103], v[32:47]
	ds_read_b128 v[124:127], v169 offset:64
	ds_read_b128 v[128:131], v169 offset:96
	ds_read_b128 v[132:135], v169 offset:6720
	ds_read_b128 v[136:139], v169 offset:6752
	s_waitcnt lgkmcnt(4)
	v_mfma_f32_32x32x16_bf16 v[64:79], v[52:55], v[96:99], v[64:79]
	v_mfma_f32_32x32x16_bf16 v[48:63], v[116:119], v[100:103], v[32:47]
	v_mfma_f32_32x32x16_bf16 v[48:63], v[120:123], v[96:99], v[48:63]
	s_waitcnt lgkmcnt(1)
	v_mfma_f32_32x32x16_bf16 v[64:79], v[124:127], v[92:95], v[64:79]
	v_mfma_f32_32x32x16_bf16 v[48:63], v[132:135], v[92:95], v[48:63]
	v_mfma_f32_32x32x16_bf16 v[64:79], v[128:131], v[88:91], v[64:79]
	ds_read_b128 v[116:119], v169 offset:128
	ds_read_b128 v[120:123], v169 offset:160
	ds_read_b128 v[128:131], v169 offset:6784
	ds_read_b128 v[176:179], v169 offset:6816
	s_waitcnt lgkmcnt(3)
	v_mfma_f32_32x32x16_bf16 v[48:63], v[136:139], v[88:91], v[48:63]
	v_mfma_f32_32x32x16_bf16 v[64:79], v[116:119], v[84:87], v[64:79]
	s_mulk_i32 s21, 0x2400
	v_add_u32_e32 v116, s21, v170
	ds_read_b128 v[136:139], v116 offset:26624
	ds_read_b128 v[124:127], v116 offset:26656
	s_waitcnt lgkmcnt(3)
	v_mfma_f32_32x32x16_bf16 v[48:63], v[128:131], v[84:87], v[48:63]
	v_mfma_f32_32x32x16_bf16 v[64:79], v[120:123], v[80:83], v[64:79]
	ds_read_b128 v[132:135], v116 offset:26688
	ds_read_b128 v[120:123], v116 offset:26720
	ds_read_b128 v[144:147], v116 offset:31232
	ds_read_b128 v[140:143], v116 offset:31264
	ds_read_b128 v[128:131], v116 offset:31296
	ds_read_b128 v[116:119], v116 offset:31328
	s_waitcnt lgkmcnt(8)
	v_mfma_f32_32x32x16_bf16 v[48:63], v[176:179], v[80:83], v[48:63]
	s_add_i32 s43, s43, 1
	s_nop 10
	v_max_f32_e32 v148, v64, v48
	v_max_f32_e32 v160, v65, v49
	v_max_f32_e32 v161, v67, v51
	v_max3_f32 v176, v66, v50, v70
	v_max3_f32 v161, v161, v71, v55
	v_max3_f32 v148, v148, v68, v52
	v_max3_f32 v160, v160, v69, v53
	v_max3_f32 v176, v176, v54, v74
	v_max3_f32 v161, v161, v75, v59
	v_max3_f32 v148, v148, v72, v56
	v_max3_f32 v160, v160, v73, v57
	v_max3_f32 v176, v176, v58, v78
	v_max3_f32 v161, v161, v79, v63
	v_max3_f32 v148, v148, v76, v60
	v_max3_f32 v160, v160, v77, v61
	v_max3_f32 v161, v176, v62, v161
	v_max3_f32 v148, v148, v160, v161
	v_mov_b32_e32 v160, v148
	s_nop 1
	v_permlane32_swap_b32_e32 v148, v160
	v_max_f32_e32 v148, v148, v160
	v_cmp_lt_f32_e32 vcc, s59, v148
	s_cbranch_vccz .Lmla_norescale_e
	v_max_f32_e32 v32, v148, v148
	v_max_f32_e32 v148, 0, v32
	v_exp_f32_e64 v160, -v148
	v_add_f32_e32 v168, v168, v148
	v_xor_b32_e32 v32, 0x80000000, v168
	v_mov_b32_e32 v33, v32
	v_mov_b32_e32 v34, v32
	v_mov_b32_e32 v35, v32
	v_mov_b32_e32 v36, v32
	v_mov_b32_e32 v37, v32
	v_mov_b32_e32 v38, v32
	v_mov_b32_e32 v39, v32
	v_mov_b32_e32 v40, v32
	v_mov_b32_e32 v41, v32
	v_mov_b32_e32 v42, v32
	v_mov_b32_e32 v43, v32
	v_mov_b32_e32 v44, v32
	v_mov_b32_e32 v45, v32
	v_mov_b32_e32 v46, v32
	v_mov_b32_e32 v47, v32
	v_pk_add_f32 v[64:65], v[64:65], v[148:149] op_sel_hi:[1,0] neg_lo:[0,1] neg_hi:[0,1]
	v_pk_add_f32 v[48:49], v[48:49], v[148:149] op_sel_hi:[1,0] neg_lo:[0,1] neg_hi:[0,1]
	v_pk_add_f32 v[66:67], v[66:67], v[148:149] op_sel_hi:[1,0] neg_lo:[0,1] neg_hi:[0,1]
	v_pk_add_f32 v[50:51], v[50:51], v[148:149] op_sel_hi:[1,0] neg_lo:[0,1] neg_hi:[0,1]
	v_pk_add_f32 v[68:69], v[68:69], v[148:149] op_sel_hi:[1,0] neg_lo:[0,1] neg_hi:[0,1]
	v_pk_add_f32 v[52:53], v[52:53], v[148:149] op_sel_hi:[1,0] neg_lo:[0,1] neg_hi:[0,1]
	v_pk_add_f32 v[70:71], v[70:71], v[148:149] op_sel_hi:[1,0] neg_lo:[0,1] neg_hi:[0,1]
	v_pk_add_f32 v[54:55], v[54:55], v[148:149] op_sel_hi:[1,0] neg_lo:[0,1] neg_hi:[0,1]
	v_pk_add_f32 v[72:73], v[72:73], v[148:149] op_sel_hi:[1,0] neg_lo:[0,1] neg_hi:[0,1]
	v_pk_add_f32 v[56:57], v[56:57], v[148:149] op_sel_hi:[1,0] neg_lo:[0,1] neg_hi:[0,1]
	v_pk_add_f32 v[74:75], v[74:75], v[148:149] op_sel_hi:[1,0] neg_lo:[0,1] neg_hi:[0,1]
	v_pk_add_f32 v[58:59], v[58:59], v[148:149] op_sel_hi:[1,0] neg_lo:[0,1] neg_hi:[0,1]
	v_pk_add_f32 v[76:77], v[76:77], v[148:149] op_sel_hi:[1,0] neg_lo:[0,1] neg_hi:[0,1]
	v_pk_add_f32 v[60:61], v[60:61], v[148:149] op_sel_hi:[1,0] neg_lo:[0,1] neg_hi:[0,1]
	v_pk_add_f32 v[78:79], v[78:79], v[148:149] op_sel_hi:[1,0] neg_lo:[0,1] neg_hi:[0,1]
	v_pk_add_f32 v[62:63], v[62:63], v[148:149] op_sel_hi:[1,0] neg_lo:[0,1] neg_hi:[0,1]
	v_pk_mul_f32 v[30:31], v[30:31], v[160:161] op_sel_hi:[1,0]
	v_pk_mul_f32 v[28:29], v[28:29], v[160:161] op_sel_hi:[1,0]
	v_pk_mul_f32 v[26:27], v[26:27], v[160:161] op_sel_hi:[1,0]
	v_pk_mul_f32 v[24:25], v[24:25], v[160:161] op_sel_hi:[1,0]
	v_pk_mul_f32 v[22:23], v[22:23], v[160:161] op_sel_hi:[1,0]
	v_pk_mul_f32 v[20:21], v[20:21], v[160:161] op_sel_hi:[1,0]
	v_pk_mul_f32 v[18:19], v[18:19], v[160:161] op_sel_hi:[1,0]
	v_pk_mul_f32 v[16:17], v[16:17], v[160:161] op_sel_hi:[1,0]
	v_pk_mul_f32 v[14:15], v[14:15], v[160:161] op_sel_hi:[1,0]
	v_pk_mul_f32 v[12:13], v[12:13], v[160:161] op_sel_hi:[1,0]
	v_pk_mul_f32 v[10:11], v[10:11], v[160:161] op_sel_hi:[1,0]
	v_pk_mul_f32 v[8:9], v[8:9], v[160:161] op_sel_hi:[1,0]
	v_pk_mul_f32 v[6:7], v[6:7], v[160:161] op_sel_hi:[1,0]
	v_pk_mul_f32 v[4:5], v[4:5], v[160:161] op_sel_hi:[1,0]
	v_pk_mul_f32 v[2:3], v[2:3], v[160:161] op_sel_hi:[1,0]
	v_pk_mul_f32 v[0:1], v[0:1], v[160:161] op_sel_hi:[1,0]
	v_pk_mul_f32 v[152:153], v[152:153], v[160:161] op_sel_hi:[1,0]
	v_pk_mul_f32 v[150:151], v[150:151], v[160:161] op_sel_hi:[1,0]
; #define AT_QK_LD0(kb_) do { if constexpr (NEGM) { const LAS unsigned char* kbp_ = Kl + (kb_) * KBUF + r32 * KROWB + hi * 16; AT_KLD2(0); __builtin_amdgcn_sched_barrier(0); } } while (0)
; template <int DQK, int DV, int RH, bool NEGM> ...
;     ...
;     const int NT = nkv / 64;
;     AT_GLOAD(0); AT_LSTORE(0, 0); __syncthreads();
;     int vs_prev = 2, vs_cur = 0, vs_next = 1;
;     if (!grpB) {
;         for (int t = 0; t < NT; ++t) {
;             const int kb = t & 1;
;             if (t + 1 < NT) AT_GLOAD(t + 1);
;             f32x16 p[RH][2];
;             AT_QK_LD0(kb); AT_QK(kb); AT_VLOAD(vs_cur); AT_SOFTMAX(); AT_PV(vs_cur);
;             if (t + 1 < NT) AT_LSTORE(kb ^ 1, vs_next);
;             __syncthreads();
;             vs_prev = vs_cur; vs_cur = vs_next; vs_next = (vs_next == 2) ? 0 : vs_next + 1;
.Lmla_norescale_e:
	v_exp_f32_e32 v160, v64
	v_exp_f32_e32 v161, v65
	v_exp_f32_e32 v64, v66
	v_exp_f32_e32 v65, v67
	v_exp_f32_e32 v68, v68
	v_exp_f32_e32 v69, v69
	v_exp_f32_e32 v66, v70
	v_exp_f32_e32 v67, v71
	v_cvt_pk_bf16_f32 v176, v160, v161
	v_cvt_pk_bf16_f32 v177, v64, v65
	v_cvt_pk_bf16_f32 v178, v68, v69
	v_cvt_pk_bf16_f32 v179, v66, v67
	v_exp_f32_e32 v70, v74
	v_exp_f32_e32 v71, v75
	s_waitcnt lgkmcnt(0)
	v_mfma_f32_32x32x16_bf16 v[16:31], v[136:139], v[176:179], v[16:31]
	v_exp_f32_e32 v136, v72
	v_exp_f32_e32 v137, v73
	v_exp_f32_e32 v74, v76
	v_exp_f32_e32 v75, v77
	v_exp_f32_e32 v72, v78
	v_exp_f32_e32 v73, v79
	v_exp_f32_e32 v76, v48
	v_mfma_f32_32x32x16_bf16 v[0:15], v[144:147], v[176:179], v[0:15]
	v_cvt_pk_bf16_f32 v144, v136, v137
	v_cvt_pk_bf16_f32 v145, v70, v71
	v_cvt_pk_bf16_f32 v146, v74, v75
	v_cvt_pk_bf16_f32 v147, v72, v73
	v_exp_f32_e32 v77, v49
	v_exp_f32_e32 v48, v50
	v_exp_f32_e32 v49, v51
	v_mfma_f32_32x32x16_bf16 v[16:31], v[124:127], v[144:147], v[16:31]
	v_exp_f32_e32 v52, v52
	v_exp_f32_e32 v53, v53
	v_exp_f32_e32 v50, v54
	v_exp_f32_e32 v51, v55
	v_cvt_pk_bf16_f32 v124, v76, v77
	v_cvt_pk_bf16_f32 v125, v48, v49
	v_cvt_pk_bf16_f32 v126, v52, v53
	v_mfma_f32_32x32x16_bf16 v[0:15], v[140:143], v[144:147], v[0:15]
	v_cvt_pk_bf16_f32 v127, v50, v51
	v_exp_f32_e32 v78, v56
	v_exp_f32_e32 v79, v57
	v_exp_f32_e32 v54, v58
	v_exp_f32_e32 v55, v59
	v_exp_f32_e32 v58, v60
	v_exp_f32_e32 v59, v61
	v_mfma_f32_32x32x16_bf16 v[16:31], v[132:135], v[124:127], v[16:31]
	v_exp_f32_e32 v56, v62
	v_exp_f32_e32 v57, v63
	v_cvt_pk_bf16_f32 v60, v78, v79
	v_cvt_pk_bf16_f32 v61, v54, v55
	v_cvt_pk_bf16_f32 v62, v58, v59
	v_cvt_pk_bf16_f32 v63, v56, v57
	v_mfma_f32_32x32x16_bf16 v[0:15], v[128:131], v[124:127], v[0:15]
	v_mfma_f32_32x32x16_bf16 v[16:31], v[120:123], v[60:63], v[16:31]
	v_mfma_f32_32x32x16_bf16 v[0:15], v[116:119], v[60:63], v[0:15]
	s_waitcnt vmcnt(1)
	ds_write_b128 v244, v[104:107] offset:13312
	s_mov_b64 exec, s[8:9]
	ds_write_b128 v245, v[108:111] offset:13312
	s_mov_b64 exec, -1
	s_mul_i32 s21, s42, 0x2400
	v_add_u32_e32 v242, s21, v243
	s_waitcnt vmcnt(0)
	ds_write2_b64 v242, v[112:113], v[114:115] offset1:2
	v_pk_add_f32 v[48:49], v[64:65], v[48:49]
	v_pk_add_f32 v[60:61], v[160:161], v[76:77]
	v_pk_add_f32 v[48:49], v[152:153], v[48:49]
	v_pk_add_f32 v[50:51], v[66:67], v[50:51]
	v_pk_add_f32 v[60:61], v[150:151], v[60:61]
	v_pk_add_f32 v[52:53], v[68:69], v[52:53]
	v_pk_add_f32 v[48:49], v[50:51], v[48:49]
	v_pk_add_f32 v[50:51], v[70:71], v[54:55]
	v_pk_add_f32 v[52:53], v[52:53], v[60:61]
	v_pk_add_f32 v[60:61], v[136:137], v[78:79]
	v_pk_add_f32 v[48:49], v[50:51], v[48:49]
	v_pk_add_f32 v[50:51], v[72:73], v[56:57]
	s_add_i32 s40, s42, 1
	v_pk_add_f32 v[52:53], v[60:61], v[52:53]
	v_pk_add_f32 v[58:59], v[74:75], v[58:59]
	v_pk_add_f32 v[152:153], v[50:51], v[48:49]
	s_cmp_lg_u32 s42, 2
	v_pk_add_f32 v[150:151], v[58:59], v[52:53]
	s_cselect_b32 s40, s40, 0
	s_cmp_lg_u32 s43, 63
	s_waitcnt lgkmcnt(0)
	s_barrier
	s_cbranch_scc1 .Lmla_loop
	ds_read_b128 v[64:67], v169 offset:13312
	ds_read_b128 v[68:71], v169 offset:13344
	ds_read_b128 v[72:75], v169 offset:19968
	ds_read_b128 v[76:79], v169 offset:20000
	s_waitcnt lgkmcnt(3)
	v_mfma_f32_32x32x16_bf16 v[48:63], v[64:67], v[100:103], v[32:47]
	ds_read_b128 v[64:67], v169 offset:13376
	ds_read_b128 v[104:107], v169 offset:13408
	ds_read_b128 v[108:111], v169 offset:20032
	ds_read_b128 v[112:115], v169 offset:20064
	s_waitcnt lgkmcnt(6)
	v_mfma_f32_32x32x16_bf16 v[48:63], v[68:71], v[96:99], v[48:63]
	s_waitcnt lgkmcnt(5)
	v_mfma_f32_32x32x16_bf16 v[32:47], v[72:75], v[100:103], v[32:47]
	s_waitcnt lgkmcnt(4)
	v_mfma_f32_32x32x16_bf16 v[32:47], v[76:79], v[96:99], v[32:47]
	s_waitcnt lgkmcnt(3)
	v_mfma_f32_32x32x16_bf16 v[48:63], v[64:67], v[92:95], v[48:63]
	ds_read_b128 v[64:67], v169 offset:13440
	ds_read_b128 v[68:71], v169 offset:13472
	ds_read_b128 v[72:75], v169 offset:20096
	ds_read_b128 v[76:79], v169 offset:20128
	s_waitcnt lgkmcnt(5)
	v_mfma_f32_32x32x16_bf16 v[32:47], v[108:111], v[92:95], v[32:47]
	v_mfma_f32_32x32x16_bf16 v[48:63], v[104:107], v[88:91], v[48:63]
	s_waitcnt lgkmcnt(4)
	v_mfma_f32_32x32x16_bf16 v[32:47], v[112:115], v[88:91], v[32:47]
	s_waitcnt lgkmcnt(3)
	v_mfma_f32_32x32x16_bf16 v[48:63], v[64:67], v[84:87], v[48:63]
	v_add3_u32 v64, v167, s21, v173
	v_add_u32_e32 v65, 0x6800, v64
	ds_read_b128 v[108:111], v65
	ds_read_b128 v[104:107], v65 offset:32
	ds_read_b128 v[96:99], v65 offset:64
	ds_read_b128 v[88:91], v65 offset:96
	s_waitcnt lgkmcnt(5)
	v_mfma_f32_32x32x16_bf16 v[32:47], v[72:75], v[84:87], v[32:47]
	ds_read_b128 v[112:115], v65 offset:4608
	ds_read_b128 v[100:103], v65 offset:4640
	ds_read_b128 v[92:95], v65 offset:4672
	ds_read_b128 v[84:87], v65 offset:4704
	v_mfma_f32_32x32x16_bf16 v[48:63], v[68:71], v[80:83], v[48:63]
	s_waitcnt lgkmcnt(8)
	v_mfma_f32_32x32x16_bf16 v[32:47], v[76:79], v[80:83], v[32:47]
	s_nop 11
	v_max_f32_e32 v64, v32, v32
	v_max_f32_e32 v65, v48, v48
	v_max_f32_e32 v64, v65, v64
	v_max_f32_e32 v65, v33, v33
	v_max_f32_e32 v66, v49, v49
	v_max_f32_e32 v65, v66, v65
	v_max_f32_e32 v66, v35, v35
	v_max_f32_e32 v67, v51, v51
	v_max_f32_e32 v66, v67, v66
	v_max3_f32 v67, v50, v34, v54
	v_max3_f32 v66, v66, v55, v39
	v_max3_f32 v64, v64, v52, v36
	v_max3_f32 v65, v65, v53, v37
	v_max3_f32 v67, v67, v38, v58
	v_max3_f32 v66, v66, v59, v43
	v_max3_f32 v64, v64, v56, v40
	v_max3_f32 v65, v65, v57, v41
	v_max3_f32 v67, v67, v42, v62
	v_max3_f32 v66, v66, v63, v47
	v_max3_f32 v64, v64, v60, v44
	v_max3_f32 v65, v65, v61, v45
	v_max3_f32 v66, v67, v46, v66
	v_max3_f32 v64, v64, v65, v66
	v_mov_b32_e32 v65, v64
	s_nop 1
	v_permlane32_swap_b32_e32 v64, v65
	v_max_f32_e32 v65, v65, v65
	v_max_f32_e32 v64, v64, v64
	v_max_f32_e32 v64, v64, v65
	v_cmp_lt_f32_e32 vcc, s59, v64
	s_cbranch_vccnz .LBB0_861
	v_mov_b32_e32 v64, v151
	v_mov_b32_e32 v151, v152
	v_mov_b32_e32 v65, v153
	s_branch .LBB0_862
